# v20: HGRN pass B LDS XOR swizzle (fragment reads conflict free) on top of v19
# speedup vs baseline: 1.0084x; 1.0084x over previous
; __device__ __forceinline__ unsigned f2bf(float f) { return pk2(f, 0.f) & 0xffffu; }
; template <bool PA>
; __device__ __forceinline__ void hgrn_scan(unsigned char* lds, const bf16* Q, const bf16* FFb, const bf16* FBb, const bf16* Ib, bf16* OFb, bf16* OBb, const float* lbp, float* segm, int slab, int tid) {
;     const int lane = tid & 63, wave = tid >> 6, r16 = lane & 15, kq = lane >> 4;
;     bf16* qin = (bf16*)lds;
;     bf16* kin = qin + 64 * 136;
;     bf16* kinT = kin + 64 * 136;
;     bf16* Pm = kinT + 128 * 72;
;     bf16* iT = Pm + 64 * 72;
;     bf16* SbT = iT + 128 * 72;
;     float* tot = (float*)(SbT + 128 * 136);
;     float* c1 = tot + 512; float* c2 = c1 + 128; float* gtv = c2 + 128;
;     const int G = slab == 0 ? 8 : 16, nch = slab == 0 ? 129 : 257;
;     const int c = tid & 127, seg = tid >> 7;
;     const int jr = tid >> 3, part = tid & 7;
;     for (int item = blockIdx.x; item < 256; item += gridDim.x) {
;         const int g = item % G, strm = item / G; const int p0 = g == 0 ? 0 : 1 + 16 * g, p1 = 17 + 16 * g;
;         if (PA && g == G - 1) continue;
;         const int dir = strm & 1, head = (strm >> 1) & 7, sq = strm >> 4;
;     ...
;                 { const int cc = 16 * wave + 4 * kq; const float s0 = c1[cc], s1 = c1[cc + 1], s2 = c1[cc + 2], s3 = c1[cc + 3];
; #pragma unroll
;                   for (int vt = 0; vt < 8; ++vt) { u32x2_t w; w.x = pk2(s0 * S[vt][0], s1 * S[vt][1]); w.y = pk2(s2 * S[vt][2], s3 * S[vt][3]); *(u32x2_t*)(SbT + (16 * vt + r16) * 136 + cc) = w; } }
;                 { const int tt = wave >> 1;
; #pragma unroll
;                   for (int si = 0; si < 2; ++si) { const int ss = 2 * (wave & 1) + si; f32x4_t ac = (f32x4_t){0.f, 0.f, 0.f, 0.f};
; #pragma unroll
;                       for (int kk = 0; kk < 4; ++kk) { const bf16x8_t av = *(const bf16x8_t*)(qin + (16 * tt + r16) * 136 + 32 * kk + 8 * kq); const bf16x8_t bv = *(const bf16x8_t*)(kin + (16 * ss + r16) * 136 + 32 * kk + 8 * kq);
;                           ac = __builtin_amdgcn_mfma_f32_16x16x32_bf16(av, bv, ac, 0, 0, 0); }
; #pragma unroll
;                       for (int e = 0; e < 4; ++e) { const int t = 16 * tt + 4 * kq + e, s = 16 * ss + r16; Pm[t * 72 + s] = (bf16)f2bf(s <= t ? ac[e] : 0.f); } } }
;                 __syncthreads();
;             }
;             f32x4_t kv[8];
.LBB0_664:
	s_cmp_lt_i32 s65, 1
	s_mov_b64 s[0:1], -1
	s_cbranch_scc1 .LBB0_753
	s_cmp_gt_i32 s65, 1
	s_cbranch_scc0 .LBB0_691
	v_readlane_b32 s0, v253, 2
	v_readlane_b32 s1, v253, 3
	s_andn2_b64 vcc, exec, s[0:1]
	s_cbranch_vccnz .LBB0_690
	v_lshlrev_b32_e32 v0, 4, v203
	s_add_u32 s2, s6, 0x730000
	v_and_b32_e32 v2, 0x70, v0
	s_addc_u32 s58, s7, 0
	v_lshlrev_b32_e32 v0, 1, v2
	s_cmp_eq_u32 s40, 0
	s_movk_i32 s8, 0x81
	v_and_b32_e32 v66, 0x7f, v202
	v_lshl_add_u64 v[4:5], s[6:7], 0, v[0:1]
	s_mov_b64 s[10:11], 0x7980000
	s_cselect_b32 s60, s8, 0x101
	v_readlane_b32 s8, v254, 22
	s_waitcnt lgkmcnt(0)
	v_lshl_add_u64 v[70:71], v[4:5], 0, s[10:11]
	v_lshlrev_b32_e32 v4, 2, v66
	v_bfe_u32 v6, v203, 4, 2
	v_ashrrev_i32_e32 v8, 6, v202
	v_lshl_add_u32 v90, v202, 2, s8
	v_add_u32_e32 v92, s8, v4
	s_movk_i32 s8, 0x80
	v_ashrrev_i32_e32 v67, 7, v202
	v_lshlrev_b32_e32 v7, 4, v8
	v_lshlrev_b32_e32 v9, 2, v6
	v_cmp_gt_u32_e64 s[36:37], s8, v202
	s_movk_i32 s8, 0x7f
	v_ashrrev_i32_e32 v88, 3, v202
	v_and_b32_e32 v3, 15, v203
	v_or_b32_e32 v68, v9, v7
	v_lshlrev_b32_e32 v89, 4, v67
	v_cmp_lt_u32_e64 s[38:39], s8, v202
	v_readlane_b32 s11, v254, 23
	v_readlane_b32 s12, v254, 24
	v_readlane_b32 s8, v254, 25
	v_lshlrev_b32_e32 v6, 4, v6
	v_lshlrev_b32_e32 v5, 1, v88
	v_add_u32_e32 v93, s11, v4
	v_add_u32_e32 v94, s12, v4
	v_add_u32_e32 v95, s8, v4
	v_lshlrev_b32_e32 v11, 2, v68
	v_or_b32_e32 v14, v89, v3
	v_add_u32_e32 v4, 0, v6
	s_movk_i32 s15, 0x110
	v_or_b32_e32 v15, v7, v3
	v_and_b32_e32 v7, 48, v7
	v_add_u32_e32 v96, s8, v11
	v_mad_u64_u32 v[72:73], s[8:9], v14, s15, v[4:5]
	s_movk_i32 s10, 0x90
	v_or_b32_e32 v16, v7, v3
	v_readlane_b32 s13, v254, 37
	v_mad_u64_u32 v[74:75], s[8:9], v15, s10, v[4:5]
	v_mad_u32_u24 v73, v16, s10, v4
	v_lshl_add_u32 v75, v16, 7, v73
	v_add_u32_e32 v16, s13, v6
	v_mul_lo_u32 v6, v88, s15
	v_add3_u32 v97, 0, v6, v0
	v_mul_u32_u24_e32 v0, 0x48, v2
	s_cselect_b32 s59, 8, 16
	v_lshlrev_b32_e32 v0, 1, v0
	v_mul_u32_u24_e32 v10, 0x90, v66
	v_add3_u32 v129, 0, v5, v0
	v_add3_u32 v130, 0, v0, v5
	v_lshlrev_b32_e32 v0, 5, v67
	s_movk_i32 s8, 0x880
	v_cvt_f32_ubyte0_e32 v23, s59
	v_lshlrev_b32_e32 v13, 5, v8
	v_or_b32_e32 v14, v9, v89
	v_or_b32_e32 v99, 1, v89
	v_add3_u32 v131, 0, v10, v0
	v_mul_lo_u32 v0, v67, s8
	s_movk_i32 s8, 0x88
	v_rcp_iflag_f32_e32 v23, v23
	v_or_b32_e32 v9, v7, v9
	v_mad_u64_u32 v[6:7], s[8:9], v99, s8, v[66:67]
	v_and_or_b32 v5, v13, 32, v3
	v_or_b32_e32 v13, 1, v14
	v_or_b32_e32 v18, 2, v14
	v_or_b32_e32 v19, 3, v14
	v_and_b32_e32 v15, -4, v8
	v_lshl_add_u32 v17, v3, 1, 0
	v_lshl_add_u32 v133, v6, 1, 0
	v_mul_u32_u24_e32 v6, 0x110, v5
	v_lshl_add_u32 v7, v5, 1, 0
	v_cmp_gt_i32_e64 s[40:41], v5, v14
	v_cmp_gt_i32_e64 s[42:43], v5, v13
	v_cmp_gt_i32_e64 s[44:45], v5, v18
	v_cmp_gt_i32_e64 s[46:47], v5, v19
	v_or_b32_e32 v5, 16, v5
	v_or_b32_e32 v0, v0, v66
	v_mul_lo_u32 v10, v14, s10
	v_cmp_gt_i32_e64 s[48:49], v5, v14
	v_cmp_gt_i32_e64 s[50:51], v5, v13
	v_cmp_gt_i32_e64 s[52:53], v5, v18
	v_cmp_gt_i32_e64 s[54:55], v5, v19
	v_lshl_or_b32 v5, v15, 4, v3
	v_lshl_add_u32 v14, v15, 5, v17
	v_or_b32_e32 v18, 1, v15
	v_or_b32_e32 v15, 2, v15
	v_or_b32_e32 v8, 3, v8
	v_lshl_or_b32 v76, v68, 7, v3
	v_lshl_add_u32 v132, v0, 1, 0
	v_mul_u32_u24_e32 v0, 0x110, v3
	v_mad_u32_u24 v150, v3, s10, v4
	v_lshl_or_b32 v19, v18, 4, v3
	v_lshl_add_u32 v18, v18, 5, v17
	v_lshl_or_b32 v21, v15, 4, v3
	v_lshl_add_u32 v15, v15, 5, v17
	v_lshl_or_b32 v3, v8, 4, v3
	v_lshl_add_u32 v8, v8, 5, v17
	v_mul_f32_e32 v17, 0x4f7ffffe, v23
	v_cvt_u32_f32_e32 v17, v17
	v_readlane_b32 s0, v255, 5
	v_readlane_b32 s1, v255, 6
	s_load_dwordx2 s[0:1], s[0:1], 0x40
	s_cselect_b32 s61, 3, 4
	s_sub_i32 s8, 0, s59
	v_readfirstlane_b32 s9, v17
	s_mul_i32 s8, s8, s9
	v_lshl_add_u32 v12, v68, 1, s13
	v_or_b32_e32 v78, 0x100, v76
	v_or_b32_e32 v101, 2, v89
	v_or_b32_e32 v103, 3, v89
	v_or_b32_e32 v105, 4, v89
	v_or_b32_e32 v107, 5, v89
	v_or_b32_e32 v109, 6, v89
	v_or_b32_e32 v111, 7, v89
	v_or_b32_e32 v113, 8, v89
	v_or_b32_e32 v115, 9, v89
	v_or_b32_e32 v117, 10, v89
	v_or_b32_e32 v119, 11, v89
	v_or_b32_e32 v121, 12, v89
	v_or_b32_e32 v123, 13, v89
	v_or_b32_e32 v125, 14, v89
	v_or_b32_e32 v127, 15, v89
	v_mul_lo_u32 v13, v5, s10
	v_mul_lo_u32 v5, v5, s15
	v_mul_u32_u24_e32 v9, 0x110, v9
	v_mul_lo_u32 v20, v19, s10
	v_mul_lo_u32 v19, v19, s15
	v_mul_lo_u32 v22, v21, s10
	v_mul_lo_u32 v21, v21, s15
	v_mul_lo_u32 v24, v3, s10
	v_mul_lo_u32 v3, v3, s15
	s_mul_hi_u32 s8, s9, s8
	v_sub_u32_e32 v91, 63, v88
	v_ashrrev_i32_e32 v69, 31, v68
	v_ashrrev_i32_e32 v77, 31, v76
	v_ashrrev_i32_e32 v79, 31, v78
	v_sub_u32_e32 v98, 63, v89
	v_sub_u32_e32 v100, 63, v99
	v_sub_u32_e32 v102, 63, v101
	v_sub_u32_e32 v104, 63, v103
	v_sub_u32_e32 v106, 63, v105
	v_sub_u32_e32 v108, 63, v107
	v_sub_u32_e32 v110, 63, v109
	v_sub_u32_e32 v112, 63, v111
	v_sub_u32_e32 v114, 63, v113
	v_sub_u32_e32 v116, 63, v115
	v_sub_u32_e32 v118, 63, v117
	v_sub_u32_e32 v120, 63, v119
	v_sub_u32_e32 v122, 63, v121
	v_sub_u32_e32 v124, 63, v123
	v_sub_u32_e32 v126, 63, v125
	v_sub_u32_e32 v128, 63, v127
	v_add_u32_e32 v134, 0x110, v133
	v_add_u32_e32 v135, 0x220, v133
	v_add_u32_e32 v136, 0x330, v133
	v_add_u32_e32 v137, 0x440, v133
	v_add_u32_e32 v138, 0x550, v133
	v_add_u32_e32 v139, 0x660, v133
	v_add_u32_e32 v140, 0x770, v133
	v_add_u32_e32 v141, 0x880, v133
	v_add_u32_e32 v142, 0x990, v133
	v_add_u32_e32 v143, 0xaa0, v133
	v_add_u32_e32 v144, 0xbb0, v133
	v_add_u32_e32 v145, 0xcc0, v133
	v_add_u32_e32 v148, 0xdd0, v133
	v_add_u32_e32 v149, 0xee0, v133
	v_add_u32_e32 v151, 0x900, v150
	v_add_u32_e32 v152, 0x1200, v150
	v_add_u32_e32 v153, 0x1b00, v150
	v_add_u32_e32 v154, 0x2400, v150
	v_add_u32_e32 v155, 0x2d00, v150
	s_waitcnt vmcnt(0)
; __device__ __forceinline__ unsigned pk2(float lo, float hi) { const f32x2_cv v = {lo, hi}; const bf16x2_cv b = __builtin_convertvector(v, bf16x2_cv); return __builtin_bit_cast(unsigned, b); }
; template <bool PA>
; __device__ __forceinline__ void hgrn_scan(unsigned char* lds, const bf16* Q, const bf16* FFb, const bf16* FBb, const bf16* Ib, bf16* OFb, bf16* OBb, const float* lbp, float* segm, int slab, int tid) {
;     ...
;                 { const int cc = 16 * wave + 4 * kq; const float s0 = c1[cc], s1 = c1[cc + 1], s2 = c1[cc + 2], s3 = c1[cc + 3];
; #pragma unroll
;                   for (int vt = 0; vt < 8; ++vt) { u32x2_t w; w.x = pk2(s0 * S[vt][0], s1 * S[vt][1]); w.y = pk2(s2 * S[vt][2], s3 * S[vt][3]); *(u32x2_t*)(SbT + (16 * vt + r16) * 136 + cc) = w; } }
;                 { const int tt = wave >> 1;
; #pragma unroll
;                   for (int si = 0; si < 2; ++si) { const int ss = 2 * (wave & 1) + si; f32x4_t ac = (f32x4_t){0.f, 0.f, 0.f, 0.f};
; #pragma unroll
;                       for (int kk = 0; kk < 4; ++kk) { const bf16x8_t av = *(const bf16x8_t*)(qin + (16 * tt + r16) * 136 + 32 * kk + 8 * kq); const bf16x8_t bv = *(const bf16x8_t*)(kin + (16 * ss + r16) * 136 + 32 * kk + 8 * kq);
;                           ac = __builtin_amdgcn_mfma_f32_16x16x32_bf16(av, bv, ac, 0, 0, 0); }
; #pragma unroll
;                       for (int e = 0; e < 4; ++e) { const int t = 16 * tt + 4 * kq + e, s = 16 * ss + r16; Pm[t * 72 + s] = (bf16)f2bf(s <= t ? ac[e] : 0.f); } } }
;                 __syncthreads();
;             }
;             f32x4_t kv[8];
;             { const bf16x8_t a0 = *(const bf16x8_t*)(kinT + (16 * wave + r16) * 72 + 8 * kq), a1 = *(const bf16x8_t*)(kinT + (16 * wave + r16) * 72 + 32 + 8 * kq);
; #pragma unroll
;               for (int vt = 0; vt < 8; ++vt) { kv[vt] = (f32x4_t){0.f, 0.f, 0.f, 0.f};
;                   kv[vt] = __builtin_amdgcn_mfma_f32_16x16x32_bf16(a0, *(const bf16x8_t*)(iT + (16 * vt + r16) * 72 + 8 * kq), kv[vt], 0, 0, 0);
;                   kv[vt] = __builtin_amdgcn_mfma_f32_16x16x32_bf16(a1, *(const bf16x8_t*)(iT + (16 * vt + r16) * 72 + 32 + 8 * kq), kv[vt], 0, 0, 0); } }
;             if (!PA) { const int tt = wave & 3;
; #pragma unroll
;                 for (int vi = 0; vi < 4; ++vi) { const int vt = 4 * (wave >> 2) + vi; f32x4_t o = (f32x4_t){0.f, 0.f, 0.f, 0.f};
; #pragma unroll
	v_add_u32_e32 v156, 0x3600, v150
	v_add_u32_e32 v157, 0x3f00, v150
	v_add_u32_e32 v158, s11, v11
	v_add_u32_e32 v159, s12, v11
	s_add_i32 s62, s9, s8
	s_add_i32 s63, s60, -2
	v_lshlrev_b32_e32 v80, 1, v2
	v_add_u32_e32 v160, v12, v0
	v_add_u32_e32 v161, v4, v6
	v_add_u32_e32 v162, v7, v10
	v_add_u32_e32 v163, v4, v13
	v_add_u32_e32 v164, v16, v5
	v_add_u32_e32 v165, v14, v9
	v_add_u32_e32 v166, v4, v20
	v_add_u32_e32 v167, v16, v19
	v_add_u32_e32 v168, v18, v9
	v_add_u32_e32 v169, v4, v22
	v_add_u32_e32 v170, v16, v21
	v_add_u32_e32 v171, v15, v9
	v_add_u32_e32 v172, v4, v24
	v_add_u32_e32 v173, v16, v3
	v_add_u32_e32 v174, v8, v9
	v_readfirstlane_b32 s9, v202
	v_mov_b32_e32 v133, v97
	v_mov_b32_e32 v134, v129
	v_mov_b32_e32 v135, v130
	v_mov_b32_e32 v136, v131
	v_mov_b32_e32 v137, v132
	s_mov_b32 s10, 0xff0
	s_mov_b32 s11, 0xff0
	v_cndmask_b32_e64 v148, 0, 16, s[10:11]
	s_mov_b32 s10, 0xff00000
	s_mov_b32 s11, 0xff00000
	v_cndmask_b32_e64 v149, 0, 16, s[10:11]
	v_sub_u32_e32 v148, v148, v149
	v_add_u32_e32 v72, v72, v148
	s_mov_b32 s10, 0xff0
	s_mov_b32 s11, 0xff0
	v_cndmask_b32_e64 v148, 0, 16, s[10:11]
	s_mov_b32 s10, 0xff00000
	s_mov_b32 s11, 0xff00000
	v_cndmask_b32_e64 v149, 0, 16, s[10:11]
	v_sub_u32_e32 v148, v148, v149
	v_add_u32_e32 v73, v73, v148
	s_mov_b32 s10, 0xff0
	s_mov_b32 s11, 0xff0
	v_cndmask_b32_e64 v148, 0, 16, s[10:11]
	s_mov_b32 s10, 0xff00000
	s_mov_b32 s11, 0xff00000
	v_cndmask_b32_e64 v149, 0, 16, s[10:11]
	v_sub_u32_e32 v148, v148, v149
	v_add_u32_e32 v74, v74, v148
	s_mov_b32 s10, 0xff0
	s_mov_b32 s11, 0xff0
	v_cndmask_b32_e64 v148, 0, 16, s[10:11]
	s_mov_b32 s10, 0xff00000
	s_mov_b32 s11, 0xff00000
	v_cndmask_b32_e64 v149, 0, 16, s[10:11]
	v_sub_u32_e32 v148, v148, v149
	v_add_u32_e32 v75, v75, v148
	s_mov_b32 s10, 0x0
	s_mov_b32 s11, 0xffffffff
	s_bitcmp1_b32 s9, 6
	s_cmov_b32 s10, 0xffffffff
	s_cmov_b32 s11, 0x0
	v_cndmask_b32_e64 v148, 0, 16, s[10:11]
	s_mov_b32 s10, 0x0
	s_mov_b32 s11, 0x0
	v_cndmask_b32_e64 v149, 0, 16, s[10:11]
	v_sub_u32_e32 v148, v148, v149
	v_add_u32_e32 v97, v97, v148
	s_mov_b32 s10, 0x0
	s_mov_b32 s11, 0x0
	v_cndmask_b32_e64 v148, 0, 16, s[10:11]
	s_mov_b32 s10, 0x0
	s_mov_b32 s11, 0xffffffff
	s_bitcmp1_b32 s9, 6
	s_cmov_b32 s10, 0xffffffff
	s_cmov_b32 s11, 0x0
	v_cndmask_b32_e64 v149, 0, 16, s[10:11]
	v_sub_u32_e32 v148, v148, v149
	v_add_u32_e32 v133, v133, v148
	s_mov_b32 s10, 0xffffffff
	s_mov_b32 s11, 0xffffffff
	s_bitcmp1_b32 s9, 6
	s_cmov_b32 s10, 0x0
	s_cmov_b32 s11, 0x0
	v_cndmask_b32_e64 v148, 0, 16, s[10:11]
	s_mov_b32 s10, 0x0
	s_mov_b32 s11, 0x0
	s_bitcmp1_b32 s9, 6
	s_cmov_b32 s10, 0xffffffff
	s_cmov_b32 s11, 0xffffffff
	v_cndmask_b32_e64 v149, 0, 16, s[10:11]
	v_sub_u32_e32 v148, v148, v149
	v_add_u32_e32 v134, v134, v148
	s_mov_b32 s10, 0xffffffff
	s_mov_b32 s11, 0xffffffff
	s_bitcmp1_b32 s9, 6
	s_cmov_b32 s10, 0x0
	s_cmov_b32 s11, 0x0
	v_cndmask_b32_e64 v148, 0, 16, s[10:11]
	s_mov_b32 s10, 0x0
	s_mov_b32 s11, 0x0
	s_bitcmp1_b32 s9, 6
	s_cmov_b32 s10, 0xffffffff
	s_cmov_b32 s11, 0xffffffff
	v_cndmask_b32_e64 v149, 0, 16, s[10:11]
	v_sub_u32_e32 v148, v148, v149
	v_add_u32_e32 v135, v135, v148
	s_mov_b32 s10, 0xff00ff0
	s_mov_b32 s11, 0xff00ff0
	v_cndmask_b32_e64 v148, 0, 16, s[10:11]
	s_mov_b32 s10, 0x0
	s_mov_b32 s11, 0x0
	v_cndmask_b32_e64 v149, 0, 16, s[10:11]
	v_sub_u32_e32 v148, v148, v149
	v_add_u32_e32 v131, v131, v148
	s_mov_b32 s10, 0x0
	s_mov_b32 s11, 0x0
	v_cndmask_b32_e64 v148, 0, 16, s[10:11]
	s_mov_b32 s10, 0xff00ff0
	s_mov_b32 s11, 0xff00ff0
	v_cndmask_b32_e64 v149, 0, 16, s[10:11]
	v_sub_u32_e32 v148, v148, v149
	v_add_u32_e32 v136, v136, v148
	s_mov_b32 s10, 0xff00ff
	s_mov_b32 s11, 0xff00ff
	v_cndmask_b32_e64 v148, 0, 16, s[10:11]
	s_mov_b32 s10, 0xff00ff00
	s_mov_b32 s11, 0xff00ff00
	v_cndmask_b32_e64 v149, 0, 16, s[10:11]
	v_sub_u32_e32 v148, v148, v149
	v_add_u32_e32 v137, v137, v148
	s_mov_b32 s10, 0xff0
	s_mov_b32 s11, 0xff0
	v_cndmask_b32_e64 v148, 0, 16, s[10:11]
	s_mov_b32 s10, 0xff00000
	s_mov_b32 s11, 0xff00000
	v_cndmask_b32_e64 v149, 0, 16, s[10:11]
	v_sub_u32_e32 v148, v148, v149
	v_add_u32_e32 v150, v150, v148
	s_mov_b32 s10, 0xff0
	s_mov_b32 s11, 0xff0
	v_cndmask_b32_e64 v148, 0, 16, s[10:11]
	s_mov_b32 s10, 0xff00000
	s_mov_b32 s11, 0xff00000
	v_cndmask_b32_e64 v149, 0, 16, s[10:11]
	v_sub_u32_e32 v148, v148, v149
	v_add_u32_e32 v151, v151, v148
	s_mov_b32 s10, 0xff0
	s_mov_b32 s11, 0xff0
	v_cndmask_b32_e64 v148, 0, 16, s[10:11]
	s_mov_b32 s10, 0xff00000
	s_mov_b32 s11, 0xff00000
	v_cndmask_b32_e64 v149, 0, 16, s[10:11]
	v_sub_u32_e32 v148, v148, v149
	v_add_u32_e32 v152, v152, v148
	s_mov_b32 s10, 0xff0
	s_mov_b32 s11, 0xff0
	v_cndmask_b32_e64 v148, 0, 16, s[10:11]
	s_mov_b32 s10, 0xff00000
	s_mov_b32 s11, 0xff00000
; __device__ __forceinline__ unsigned pk2(float lo, float hi) { const f32x2_cv v = {lo, hi}; const bf16x2_cv b = __builtin_convertvector(v, bf16x2_cv); return __builtin_bit_cast(unsigned, b); }
; template <bool PA>
; __device__ __forceinline__ void hgrn_scan(unsigned char* lds, const bf16* Q, const bf16* FFb, const bf16* FBb, const bf16* Ib, bf16* OFb, bf16* OBb, const float* lbp, float* segm, int slab, int tid) {
;     ...
;                 { const int cc = 16 * wave + 4 * kq; const float s0 = c1[cc], s1 = c1[cc + 1], s2 = c1[cc + 2], s3 = c1[cc + 3];
; #pragma unroll
;                   for (int vt = 0; vt < 8; ++vt) { u32x2_t w; w.x = pk2(s0 * S[vt][0], s1 * S[vt][1]); w.y = pk2(s2 * S[vt][2], s3 * S[vt][3]); *(u32x2_t*)(SbT + (16 * vt + r16) * 136 + cc) = w; } }
;                 { const int tt = wave >> 1;
; #pragma unroll
;                   for (int si = 0; si < 2; ++si) { const int ss = 2 * (wave & 1) + si; f32x4_t ac = (f32x4_t){0.f, 0.f, 0.f, 0.f};
; #pragma unroll
;                       for (int kk = 0; kk < 4; ++kk) { const bf16x8_t av = *(const bf16x8_t*)(qin + (16 * tt + r16) * 136 + 32 * kk + 8 * kq); const bf16x8_t bv = *(const bf16x8_t*)(kin + (16 * ss + r16) * 136 + 32 * kk + 8 * kq);
;                           ac = __builtin_amdgcn_mfma_f32_16x16x32_bf16(av, bv, ac, 0, 0, 0); }
; #pragma unroll
;                       for (int e = 0; e < 4; ++e) { const int t = 16 * tt + 4 * kq + e, s = 16 * ss + r16; Pm[t * 72 + s] = (bf16)f2bf(s <= t ? ac[e] : 0.f); } } }
;                 __syncthreads();
;             }
;             f32x4_t kv[8];
;             { const bf16x8_t a0 = *(const bf16x8_t*)(kinT + (16 * wave + r16) * 72 + 8 * kq), a1 = *(const bf16x8_t*)(kinT + (16 * wave + r16) * 72 + 32 + 8 * kq);
; #pragma unroll
;               for (int vt = 0; vt < 8; ++vt) { kv[vt] = (f32x4_t){0.f, 0.f, 0.f, 0.f};
;                   kv[vt] = __builtin_amdgcn_mfma_f32_16x16x32_bf16(a0, *(const bf16x8_t*)(iT + (16 * vt + r16) * 72 + 8 * kq), kv[vt], 0, 0, 0);
;                   kv[vt] = __builtin_amdgcn_mfma_f32_16x16x32_bf16(a1, *(const bf16x8_t*)(iT + (16 * vt + r16) * 72 + 32 + 8 * kq), kv[vt], 0, 0, 0); } }
;             if (!PA) { const int tt = wave & 3;
; #pragma unroll
;                 for (int vi = 0; vi < 4; ++vi) { const int vt = 4 * (wave >> 2) + vi; f32x4_t o = (f32x4_t){0.f, 0.f, 0.f, 0.f};
; #pragma unroll
	v_cndmask_b32_e64 v149, 0, 16, s[10:11]
	v_sub_u32_e32 v148, v148, v149
	v_add_u32_e32 v153, v153, v148
	s_mov_b32 s10, 0xff0
	s_mov_b32 s11, 0xff0
	v_cndmask_b32_e64 v148, 0, 16, s[10:11]
	s_mov_b32 s10, 0xff00000
	s_mov_b32 s11, 0xff00000
	v_cndmask_b32_e64 v149, 0, 16, s[10:11]
	v_sub_u32_e32 v148, v148, v149
	v_add_u32_e32 v154, v154, v148
	s_mov_b32 s10, 0xff0
	s_mov_b32 s11, 0xff0
	v_cndmask_b32_e64 v148, 0, 16, s[10:11]
	s_mov_b32 s10, 0xff00000
	s_mov_b32 s11, 0xff00000
	v_cndmask_b32_e64 v149, 0, 16, s[10:11]
	v_sub_u32_e32 v148, v148, v149
	v_add_u32_e32 v155, v155, v148
	s_mov_b32 s10, 0xff0
	s_mov_b32 s11, 0xff0
	v_cndmask_b32_e64 v148, 0, 16, s[10:11]
	s_mov_b32 s10, 0xff00000
	s_mov_b32 s11, 0xff00000
	v_cndmask_b32_e64 v149, 0, 16, s[10:11]
	v_sub_u32_e32 v148, v148, v149
	v_add_u32_e32 v156, v156, v148
	s_mov_b32 s10, 0xff0
	s_mov_b32 s11, 0xff0
	v_cndmask_b32_e64 v148, 0, 16, s[10:11]
	s_mov_b32 s10, 0xff00000
	s_mov_b32 s11, 0xff00000
	v_cndmask_b32_e64 v149, 0, 16, s[10:11]
	v_sub_u32_e32 v148, v148, v149
	v_add_u32_e32 v157, v157, v148
	s_mov_b32 s10, 0xff00ff0
	s_mov_b32 s11, 0x0
	v_cndmask_b32_e64 v148, 0, 16, s[10:11]
	s_mov_b32 s10, 0x0
	s_mov_b32 s11, 0xff00ff0
	v_cndmask_b32_e64 v149, 0, 16, s[10:11]
	v_sub_u32_e32 v148, v148, v149
	v_add_u32_e32 v160, v160, v148
	s_mov_b32 s10, 0xff0
	s_mov_b32 s11, 0xff0
	v_cndmask_b32_e64 v148, 0, 16, s[10:11]
	s_mov_b32 s10, 0xff00000
	s_mov_b32 s11, 0xff00000
	v_cndmask_b32_e64 v149, 0, 16, s[10:11]
	v_sub_u32_e32 v148, v148, v149
	v_add_u32_e32 v161, v161, v148
	s_mov_b32 s10, 0xff0000
	s_mov_b32 s11, 0xff
	v_cndmask_b32_e64 v148, 0, 16, s[10:11]
	s_mov_b32 s10, 0xff000000
	s_mov_b32 s11, 0xff00
	v_cndmask_b32_e64 v149, 0, 16, s[10:11]
	v_sub_u32_e32 v148, v148, v149
	v_add_u32_e32 v162, v162, v148
	s_mov_b32 s10, 0xff0
	s_mov_b32 s11, 0xff0
	v_cndmask_b32_e64 v148, 0, 16, s[10:11]
	s_mov_b32 s10, 0xff00000
	s_mov_b32 s11, 0xff00000
	v_cndmask_b32_e64 v149, 0, 16, s[10:11]
	v_sub_u32_e32 v148, v148, v149
	v_add_u32_e32 v163, v163, v148
	s_mov_b32 s10, 0xff0
	s_mov_b32 s11, 0xff0
	v_cndmask_b32_e64 v148, 0, 16, s[10:11]
	s_mov_b32 s10, 0xff00000
	s_mov_b32 s11, 0xff00000
	v_cndmask_b32_e64 v149, 0, 16, s[10:11]
	v_sub_u32_e32 v148, v148, v149
	v_add_u32_e32 v164, v164, v148
	s_mov_b32 s10, 0xff0000
	s_mov_b32 s11, 0xff
	v_cndmask_b32_e64 v148, 0, 16, s[10:11]
	s_mov_b32 s10, 0xff000000
	s_mov_b32 s11, 0xff00
	v_cndmask_b32_e64 v149, 0, 16, s[10:11]
	v_sub_u32_e32 v148, v148, v149
	v_add_u32_e32 v165, v165, v148
	s_mov_b32 s10, 0xff0
	s_mov_b32 s11, 0xff0
	v_cndmask_b32_e64 v148, 0, 16, s[10:11]
	s_mov_b32 s10, 0xff00000
	s_mov_b32 s11, 0xff00000
	v_cndmask_b32_e64 v149, 0, 16, s[10:11]
	v_sub_u32_e32 v148, v148, v149
	v_add_u32_e32 v166, v166, v148
	s_mov_b32 s10, 0xff0
	s_mov_b32 s11, 0xff0
	v_cndmask_b32_e64 v148, 0, 16, s[10:11]
	s_mov_b32 s10, 0xff00000
	s_mov_b32 s11, 0xff00000
	v_cndmask_b32_e64 v149, 0, 16, s[10:11]
	v_sub_u32_e32 v148, v148, v149
	v_add_u32_e32 v167, v167, v148
	s_mov_b32 s10, 0xff0000
	s_mov_b32 s11, 0xff
	v_cndmask_b32_e64 v148, 0, 16, s[10:11]
	s_mov_b32 s10, 0xff000000
	s_mov_b32 s11, 0xff00
	v_cndmask_b32_e64 v149, 0, 16, s[10:11]
	v_sub_u32_e32 v148, v148, v149
	v_add_u32_e32 v168, v168, v148
	s_mov_b32 s10, 0xff0
	s_mov_b32 s11, 0xff0
	v_cndmask_b32_e64 v148, 0, 16, s[10:11]
	s_mov_b32 s10, 0xff00000
	s_mov_b32 s11, 0xff00000
	v_cndmask_b32_e64 v149, 0, 16, s[10:11]
	v_sub_u32_e32 v148, v148, v149
	v_add_u32_e32 v169, v169, v148
	s_mov_b32 s10, 0xff0
	s_mov_b32 s11, 0xff0
	v_cndmask_b32_e64 v148, 0, 16, s[10:11]
	s_mov_b32 s10, 0xff00000
	s_mov_b32 s11, 0xff00000
	v_cndmask_b32_e64 v149, 0, 16, s[10:11]
	v_sub_u32_e32 v148, v148, v149
	v_add_u32_e32 v170, v170, v148
	s_mov_b32 s10, 0xff0000
	s_mov_b32 s11, 0xff
	v_cndmask_b32_e64 v148, 0, 16, s[10:11]
	s_mov_b32 s10, 0xff000000
	s_mov_b32 s11, 0xff00
	v_cndmask_b32_e64 v149, 0, 16, s[10:11]
	v_sub_u32_e32 v148, v148, v149
	v_add_u32_e32 v171, v171, v148
	s_mov_b32 s10, 0xff0
	s_mov_b32 s11, 0xff0
	v_cndmask_b32_e64 v148, 0, 16, s[10:11]
	s_mov_b32 s10, 0xff00000
	s_mov_b32 s11, 0xff00000
	v_cndmask_b32_e64 v149, 0, 16, s[10:11]
	v_sub_u32_e32 v148, v148, v149
	v_add_u32_e32 v172, v172, v148
	s_mov_b32 s10, 0xff0
	s_mov_b32 s11, 0xff0
	v_cndmask_b32_e64 v148, 0, 16, s[10:11]
	s_mov_b32 s10, 0xff00000
	s_mov_b32 s11, 0xff00000
	v_cndmask_b32_e64 v149, 0, 16, s[10:11]
	v_sub_u32_e32 v148, v148, v149
	v_add_u32_e32 v173, v173, v148
	s_mov_b32 s10, 0xff0000
	s_mov_b32 s11, 0xff
	v_cndmask_b32_e64 v148, 0, 16, s[10:11]
	s_mov_b32 s10, 0xff000000
	s_mov_b32 s11, 0xff00
	v_cndmask_b32_e64 v149, 0, 16, s[10:11]
	v_sub_u32_e32 v148, v148, v149
	v_add_u32_e32 v174, v174, v148
	s_mov_b32 s64, s96
	s_branch .LBB0_669

; __device__ __forceinline__ unsigned pk2(float lo, float hi) { const f32x2_cv v = {lo, hi}; const bf16x2_cv b = __builtin_convertvector(v, bf16x2_cv); return __builtin_bit_cast(unsigned, b); }
; __device__ __forceinline__ unsigned f2bf(float f) { return pk2(f, 0.f) & 0xffffu; }
; template <bool PA>
; __device__ __forceinline__ void hgrn_scan(unsigned char* lds, const bf16* Q, const bf16* FFb, const bf16* FBb, const bf16* Ib, bf16* OFb, bf16* OBb, const float* lbp, float* segm, int slab, int tid) {
;     ...
;                 { const int cc = 16 * wave + 4 * kq; const float s0 = c1[cc], s1 = c1[cc + 1], s2 = c1[cc + 2], s3 = c1[cc + 3];
; #pragma unroll
;                   for (int vt = 0; vt < 8; ++vt) { u32x2_t w; w.x = pk2(s0 * S[vt][0], s1 * S[vt][1]); w.y = pk2(s2 * S[vt][2], s3 * S[vt][3]); *(u32x2_t*)(SbT + (16 * vt + r16) * 136 + cc) = w; } }
;                 { const int tt = wave >> 1;
; #pragma unroll
;                   for (int si = 0; si < 2; ++si) { const int ss = 2 * (wave & 1) + si; f32x4_t ac = (f32x4_t){0.f, 0.f, 0.f, 0.f};
; #pragma unroll
;                       for (int kk = 0; kk < 4; ++kk) { const bf16x8_t av = *(const bf16x8_t*)(qin + (16 * tt + r16) * 136 + 32 * kk + 8 * kq); const bf16x8_t bv = *(const bf16x8_t*)(kin + (16 * ss + r16) * 136 + 32 * kk + 8 * kq);
;                           ac = __builtin_amdgcn_mfma_f32_16x16x32_bf16(av, bv, ac, 0, 0, 0); }
; #pragma unroll
;                       for (int e = 0; e < 4; ++e) { const int t = 16 * tt + 4 * kq + e, s = 16 * ss + r16; Pm[t * 72 + s] = (bf16)f2bf(s <= t ? ac[e] : 0.f); } } }
;                 __syncthreads();
;             }
;             f32x4_t kv[8];
;             { const bf16x8_t a0 = *(const bf16x8_t*)(kinT + (16 * wave + r16) * 72 + 8 * kq), a1 = *(const bf16x8_t*)(kinT + (16 * wave + r16) * 72 + 32 + 8 * kq);
; #pragma unroll
;               for (int vt = 0; vt < 8; ++vt) { kv[vt] = (f32x4_t){0.f, 0.f, 0.f, 0.f};
;                   kv[vt] = __builtin_amdgcn_mfma_f32_16x16x32_bf16(a0, *(const bf16x8_t*)(iT + (16 * vt + r16) * 72 + 8 * kq), kv[vt], 0, 0, 0);
;                   kv[vt] = __builtin_amdgcn_mfma_f32_16x16x32_bf16(a1, *(const bf16x8_t*)(iT + (16 * vt + r16) * 72 + 32 + 8 * kq), kv[vt], 0, 0, 0); } }
.LBB0_675:
	s_or_b64 exec, exec, s[12:13]
	s_waitcnt lgkmcnt(0)
	s_barrier
	ds_read_b128 v[34:37], v96
	s_add_i32 s24, s24, -1
	s_and_b64 vcc, exec, s[10:11]
	s_waitcnt lgkmcnt(0)
	v_pk_mul_f32 v[38:39], v[2:3], v[34:35]
	v_pk_mul_f32 v[40:41], v[4:5], v[36:37]
	v_cvt_pk_bf16_f32 v38, v38, v39
	v_cvt_pk_bf16_f32 v39, v40, v41
	ds_write_b64 v160, v[38:39]
	v_pk_mul_f32 v[38:39], v[6:7], v[34:35]
	v_pk_mul_f32 v[40:41], v[8:9], v[36:37]
	v_cvt_pk_bf16_f32 v38, v38, v39
	v_cvt_pk_bf16_f32 v39, v40, v41
	ds_write_b64 v160, v[38:39] offset:4352
	v_pk_mul_f32 v[38:39], v[10:11], v[34:35]
	v_pk_mul_f32 v[40:41], v[12:13], v[36:37]
	v_cvt_pk_bf16_f32 v38, v38, v39
	v_cvt_pk_bf16_f32 v39, v40, v41
	ds_write_b64 v160, v[38:39] offset:8704
	v_pk_mul_f32 v[38:39], v[14:15], v[34:35]
	v_pk_mul_f32 v[40:41], v[16:17], v[36:37]
	v_cvt_pk_bf16_f32 v38, v38, v39
	v_cvt_pk_bf16_f32 v39, v40, v41
	ds_write_b64 v160, v[38:39] offset:13056
	v_pk_mul_f32 v[38:39], v[18:19], v[34:35]
	v_pk_mul_f32 v[40:41], v[20:21], v[36:37]
	v_cvt_pk_bf16_f32 v38, v38, v39
	v_cvt_pk_bf16_f32 v39, v40, v41
	ds_write_b64 v160, v[38:39] offset:17408
	v_pk_mul_f32 v[38:39], v[22:23], v[34:35]
	v_pk_mul_f32 v[40:41], v[24:25], v[36:37]
	v_cvt_pk_bf16_f32 v38, v38, v39
	v_cvt_pk_bf16_f32 v39, v40, v41
	ds_write_b64 v160, v[38:39] offset:21760
	v_pk_mul_f32 v[38:39], v[26:27], v[34:35]
	v_pk_mul_f32 v[40:41], v[28:29], v[36:37]
	v_pk_mul_f32 v[34:35], v[30:31], v[34:35]
	v_pk_mul_f32 v[36:37], v[32:33], v[36:37]
	v_cvt_pk_bf16_f32 v38, v38, v39
	v_cvt_pk_bf16_f32 v39, v40, v41
	v_cvt_pk_bf16_f32 v34, v34, v35
	v_cvt_pk_bf16_f32 v35, v36, v37
	ds_write_b64 v160, v[38:39] offset:26112
	ds_write_b64 v160, v[34:35] offset:30464
	ds_read_b128 v[34:37], v72
	ds_read_b128 v[38:41], v161 offset:17408
	s_waitcnt lgkmcnt(0)
	v_mfma_f32_16x16x32_bf16 v[34:37], v[34:37], v[38:41], 0
	ds_read_b128 v[38:41], v72 offset:64
	ds_read_b128 v[42:45], v161 offset:17472
	s_waitcnt lgkmcnt(0)
	v_mfma_f32_16x16x32_bf16 v[34:37], v[38:41], v[42:45], v[34:37]
	ds_read_b128 v[38:41], v72 offset:128
	ds_read_b128 v[42:45], v161 offset:17536
	s_waitcnt lgkmcnt(0)
	v_mfma_f32_16x16x32_bf16 v[34:37], v[38:41], v[42:45], v[34:37]
	ds_read_b128 v[38:41], v72 offset:192
	ds_read_b128 v[42:45], v161 offset:17600
	s_waitcnt lgkmcnt(0)
	v_mfma_f32_16x16x32_bf16 v[34:37], v[38:41], v[42:45], v[34:37]
	s_nop 7
	v_cvt_pk_bf16_f32 v34, v34, s0
	v_cndmask_b32_e64 v34, v34, 0, s[40:41]
	ds_write_b16 v162, v34 offset:53248
	v_cvt_pk_bf16_f32 v34, v35, s0
	v_cndmask_b32_e64 v34, v34, 0, s[42:43]
	ds_write_b16 v162, v34 offset:53392
	v_cvt_pk_bf16_f32 v34, v36, s0
	v_cndmask_b32_e64 v34, v34, 0, s[44:45]
	ds_write_b16 v162, v34 offset:53536
	v_cvt_pk_bf16_f32 v34, v37, s0
	v_cndmask_b32_e64 v34, v34, 0, s[46:47]
	ds_write_b16 v162, v34 offset:53680
	ds_read_b128 v[34:37], v72
	ds_read_b128 v[38:41], v161 offset:21760
	s_waitcnt lgkmcnt(0)
	v_mfma_f32_16x16x32_bf16 v[34:37], v[34:37], v[38:41], 0
	ds_read_b128 v[38:41], v72 offset:64
	ds_read_b128 v[42:45], v161 offset:21824
	s_waitcnt lgkmcnt(0)
	v_mfma_f32_16x16x32_bf16 v[34:37], v[38:41], v[42:45], v[34:37]
	ds_read_b128 v[38:41], v72 offset:128
	ds_read_b128 v[42:45], v161 offset:21888
	s_waitcnt lgkmcnt(0)
	v_mfma_f32_16x16x32_bf16 v[34:37], v[38:41], v[42:45], v[34:37]
	ds_read_b128 v[38:41], v72 offset:192
	ds_read_b128 v[42:45], v161 offset:21952
	s_waitcnt lgkmcnt(0)
	v_mfma_f32_16x16x32_bf16 v[34:37], v[38:41], v[42:45], v[34:37]
	s_nop 7
	v_cvt_pk_bf16_f32 v34, v34, s0
	v_cndmask_b32_e64 v34, v34, 0, s[48:49]
	ds_write_b16 v162, v34 offset:53280
	v_cvt_pk_bf16_f32 v34, v35, s0
	v_cndmask_b32_e64 v34, v34, 0, s[50:51]
	ds_write_b16 v162, v34 offset:53424
	v_cvt_pk_bf16_f32 v34, v36, s0
	v_cndmask_b32_e64 v34, v34, 0, s[52:53]
	ds_write_b16 v162, v34 offset:53568
	v_cvt_pk_bf16_f32 v34, v37, s0
	v_cndmask_b32_e64 v34, v34, 0, s[54:55]
	ds_write_b16 v162, v34 offset:53712
	s_waitcnt lgkmcnt(0)
	s_barrier
	ds_read_b128 v[34:37], v74 offset:34816
	ds_read_b128 v[234:237], v74 offset:34880
	ds_read_b128 v[38:41], v150 offset:62464
	ds_read_b128 v[42:45], v150 offset:62528
	ds_read_b128 v[238:241], v156 offset:62528
	s_waitcnt lgkmcnt(2)
	v_mfma_f32_16x16x32_bf16 v[38:41], v[34:37], v[38:41], 0
	s_waitcnt lgkmcnt(1)
	v_mfma_f32_16x16x32_bf16 v[62:65], v[234:237], v[42:45], v[38:41]
	ds_read_b128 v[42:45], v151 offset:62528
	s_nop 4
	ds_read_b128 v[38:41], v151 offset:62464
	s_waitcnt lgkmcnt(0)
	v_mfma_f32_16x16x32_bf16 v[38:41], v[34:37], v[38:41], 0
	v_mfma_f32_16x16x32_bf16 v[46:49], v[234:237], v[42:45], v[38:41]
	ds_read_b128 v[42:45], v152 offset:62528
	s_nop 5
	ds_read_b128 v[38:41], v152 offset:62464
	s_waitcnt lgkmcnt(0)
	v_mfma_f32_16x16x32_bf16 v[38:41], v[34:37], v[38:41], 0
	v_mfma_f32_16x16x32_bf16 v[50:53], v[234:237], v[42:45], v[38:41]
	ds_read_b128 v[42:45], v153 offset:62528
	s_nop 5
	ds_read_b128 v[38:41], v153 offset:62464
	s_waitcnt lgkmcnt(0)
	v_mfma_f32_16x16x32_bf16 v[38:41], v[34:37], v[38:41], 0
	v_mfma_f32_16x16x32_bf16 v[54:57], v[234:237], v[42:45], v[38:41]
	ds_read_b128 v[42:45], v154 offset:62528
	s_nop 5
	ds_read_b128 v[38:41], v154 offset:62464
	s_waitcnt lgkmcnt(0)
	v_mfma_f32_16x16x32_bf16 v[38:41], v[34:37], v[38:41], 0
	v_mfma_f32_16x16x32_bf16 v[58:61], v[234:237], v[42:45], v[38:41]
	ds_read_b128 v[42:45], v155 offset:62528
	s_nop 5
	ds_read_b128 v[38:41], v155 offset:62464
	s_waitcnt lgkmcnt(0)
	v_mfma_f32_16x16x32_bf16 v[38:41], v[34:37], v[38:41], 0
	v_mfma_f32_16x16x32_bf16 v[42:45], v[234:237], v[42:45], v[38:41]
	s_nop 6
	ds_read_b128 v[38:41], v156 offset:62464
	s_waitcnt lgkmcnt(0)
; __device__ __forceinline__ unsigned f2bf(float f) { return pk2(f, 0.f) & 0xffffu; }
; template <bool PA>
; __device__ __forceinline__ void hgrn_scan(unsigned char* lds, const bf16* Q, const bf16* FFb, const bf16* FBb, const bf16* Ib, bf16* OFb, bf16* OBb, const float* lbp, float* segm, int slab, int tid) {
;     ...
;             f32x4_t kv[8];
;             { const bf16x8_t a0 = *(const bf16x8_t*)(kinT + (16 * wave + r16) * 72 + 8 * kq), a1 = *(const bf16x8_t*)(kinT + (16 * wave + r16) * 72 + 32 + 8 * kq);
; #pragma unroll
;               for (int vt = 0; vt < 8; ++vt) { kv[vt] = (f32x4_t){0.f, 0.f, 0.f, 0.f};
;                   kv[vt] = __builtin_amdgcn_mfma_f32_16x16x32_bf16(a0, *(const bf16x8_t*)(iT + (16 * vt + r16) * 72 + 8 * kq), kv[vt], 0, 0, 0);
;                   kv[vt] = __builtin_amdgcn_mfma_f32_16x16x32_bf16(a1, *(const bf16x8_t*)(iT + (16 * vt + r16) * 72 + 32 + 8 * kq), kv[vt], 0, 0, 0); } }
;             if (!PA) { const int tt = wave & 3;
; #pragma unroll
;                 for (int vi = 0; vi < 4; ++vi) { const int vt = 4 * (wave >> 2) + vi; f32x4_t o = (f32x4_t){0.f, 0.f, 0.f, 0.f};
; #pragma unroll
;                     for (int kk = 0; kk < 2; ++kk) o = __builtin_amdgcn_mfma_f32_16x16x32_bf16(*(const bf16x8_t*)(Pm + (16 * tt + r16) * 72 + 32 * kk + 8 * kq), *(const bf16x8_t*)(iT + (16 * vt + r16) * 72 + 32 * kk + 8 * kq), o, 0, 0, 0);
; #pragma unroll
;                     for (int kk = 0; kk < 4; ++kk) o = __builtin_amdgcn_mfma_f32_16x16x32_bf16(*(const bf16x8_t*)(qin + (16 * tt + r16) * 136 + 32 * kk + 8 * kq), *(const bf16x8_t*)(SbT + (16 * vt + r16) * 136 + 32 * kk + 8 * kq), o, 0, 0, 0);
; #pragma unroll
;                     for (int e = 0; e < 4; ++e) kin[(16 * tt + 4 * kq + e) * 136 + 16 * vt + r16] = (bf16)f2bf(o[e]); } }
;             { const int cc = 16 * wave + 4 * kq;
; #pragma unroll
;               for (int e = 0; e < 4; ++e) { const float ge = gtv[cc + e], ce = c2[cc + e];
	v_mfma_f32_16x16x32_bf16 v[38:41], v[34:37], v[38:41], 0
	v_mfma_f32_16x16x32_bf16 v[38:41], v[234:237], v[238:241], v[38:41]
	ds_read_b128 v[238:241], v157 offset:62464
	s_waitcnt lgkmcnt(0)
	v_mfma_f32_16x16x32_bf16 v[34:37], v[34:37], v[238:241], 0
	ds_read_b128 v[238:241], v157 offset:62528
	s_waitcnt lgkmcnt(0)
	v_mfma_f32_16x16x32_bf16 v[34:37], v[234:237], v[238:241], v[34:37]
	ds_read_b128 v[234:237], v73 offset:53248
	ds_read_b128 v[238:241], v163 offset:62464
	s_waitcnt lgkmcnt(0)
	v_mfma_f32_16x16x32_bf16 v[234:237], v[234:237], v[238:241], 0
	ds_read_b128 v[238:241], v73 offset:53312
	ds_read_b128 v[242:245], v163 offset:62528
	s_waitcnt lgkmcnt(0)
	v_mfma_f32_16x16x32_bf16 v[234:237], v[238:241], v[242:245], v[234:237]
	ds_read_b128 v[238:241], v75
	ds_read_b128 v[242:245], v164
	s_waitcnt lgkmcnt(0)
	v_mfma_f32_16x16x32_bf16 v[234:237], v[238:241], v[242:245], v[234:237]
	ds_read_b128 v[238:241], v75 offset:64
	ds_read_b128 v[242:245], v164 offset:64
	s_waitcnt lgkmcnt(0)
	v_mfma_f32_16x16x32_bf16 v[234:237], v[238:241], v[242:245], v[234:237]
	ds_read_b128 v[238:241], v75 offset:128
	ds_read_b128 v[242:245], v164 offset:128
	s_waitcnt lgkmcnt(0)
	v_mfma_f32_16x16x32_bf16 v[234:237], v[238:241], v[242:245], v[234:237]
	ds_read_b128 v[238:241], v75 offset:192
	ds_read_b128 v[242:245], v164 offset:192
	s_waitcnt lgkmcnt(0)
	v_mfma_f32_16x16x32_bf16 v[234:237], v[238:241], v[242:245], v[234:237]
	s_nop 7
	v_cvt_pk_bf16_f32 v146, v234, s0
	ds_write_b16 v165, v146 offset:17408
	v_cvt_pk_bf16_f32 v146, v235, s0
	ds_write_b16 v165, v146 offset:17680
	v_cvt_pk_bf16_f32 v146, v236, s0
	ds_write_b16 v165, v146 offset:17952
	v_cvt_pk_bf16_f32 v146, v237, s0
	ds_write_b16 v165, v146 offset:18224
	ds_read_b128 v[234:237], v73 offset:53248
	ds_read_b128 v[238:241], v166 offset:62464
	s_waitcnt lgkmcnt(0)
	v_mfma_f32_16x16x32_bf16 v[234:237], v[234:237], v[238:241], 0
	ds_read_b128 v[238:241], v73 offset:53312
	ds_read_b128 v[242:245], v166 offset:62528
	s_waitcnt lgkmcnt(0)
	v_mfma_f32_16x16x32_bf16 v[234:237], v[238:241], v[242:245], v[234:237]
	ds_read_b128 v[238:241], v75
	ds_read_b128 v[242:245], v167
	s_waitcnt lgkmcnt(0)
	v_mfma_f32_16x16x32_bf16 v[234:237], v[238:241], v[242:245], v[234:237]
	ds_read_b128 v[238:241], v75 offset:64
	ds_read_b128 v[242:245], v167 offset:64
	s_waitcnt lgkmcnt(0)
	v_mfma_f32_16x16x32_bf16 v[234:237], v[238:241], v[242:245], v[234:237]
	ds_read_b128 v[238:241], v75 offset:128
	ds_read_b128 v[242:245], v167 offset:128
	s_waitcnt lgkmcnt(0)
	v_mfma_f32_16x16x32_bf16 v[234:237], v[238:241], v[242:245], v[234:237]
	ds_read_b128 v[238:241], v75 offset:192
	ds_read_b128 v[242:245], v167 offset:192
	s_waitcnt lgkmcnt(0)
	v_mfma_f32_16x16x32_bf16 v[234:237], v[238:241], v[242:245], v[234:237]
	s_nop 7
	v_cvt_pk_bf16_f32 v146, v234, s0
	ds_write_b16 v168, v146 offset:17408
	v_cvt_pk_bf16_f32 v146, v235, s0
	ds_write_b16 v168, v146 offset:17680
	v_cvt_pk_bf16_f32 v146, v236, s0
	ds_write_b16 v168, v146 offset:17952
	v_cvt_pk_bf16_f32 v146, v237, s0
	ds_write_b16 v168, v146 offset:18224
	ds_read_b128 v[234:237], v73 offset:53248
	ds_read_b128 v[238:241], v169 offset:62464
	s_waitcnt lgkmcnt(0)
	v_mfma_f32_16x16x32_bf16 v[234:237], v[234:237], v[238:241], 0
	ds_read_b128 v[238:241], v73 offset:53312
	ds_read_b128 v[242:245], v169 offset:62528
	s_waitcnt lgkmcnt(0)
	v_mfma_f32_16x16x32_bf16 v[234:237], v[238:241], v[242:245], v[234:237]
	ds_read_b128 v[238:241], v75
	ds_read_b128 v[242:245], v170
	s_waitcnt lgkmcnt(0)
	v_mfma_f32_16x16x32_bf16 v[234:237], v[238:241], v[242:245], v[234:237]
	ds_read_b128 v[238:241], v75 offset:64
	ds_read_b128 v[242:245], v170 offset:64
	s_waitcnt lgkmcnt(0)
	v_mfma_f32_16x16x32_bf16 v[234:237], v[238:241], v[242:245], v[234:237]
	ds_read_b128 v[238:241], v75 offset:128
	ds_read_b128 v[242:245], v170 offset:128
	s_waitcnt lgkmcnt(0)
	v_mfma_f32_16x16x32_bf16 v[234:237], v[238:241], v[242:245], v[234:237]
	ds_read_b128 v[238:241], v75 offset:192
	ds_read_b128 v[242:245], v170 offset:192
	s_waitcnt lgkmcnt(0)
	v_mfma_f32_16x16x32_bf16 v[234:237], v[238:241], v[242:245], v[234:237]
	s_nop 7
	v_cvt_pk_bf16_f32 v146, v234, s0
	ds_write_b16 v171, v146 offset:17408
	v_cvt_pk_bf16_f32 v146, v235, s0
	ds_write_b16 v171, v146 offset:17680
	v_cvt_pk_bf16_f32 v146, v236, s0
	ds_write_b16 v171, v146 offset:17952
	v_cvt_pk_bf16_f32 v146, v237, s0
	ds_write_b16 v171, v146 offset:18224
	ds_read_b128 v[234:237], v73 offset:53248
	ds_read_b128 v[238:241], v172 offset:62464
	s_waitcnt lgkmcnt(0)
	v_mfma_f32_16x16x32_bf16 v[234:237], v[234:237], v[238:241], 0
	ds_read_b128 v[238:241], v73 offset:53312
	ds_read_b128 v[242:245], v172 offset:62528
	s_waitcnt lgkmcnt(0)
	v_mfma_f32_16x16x32_bf16 v[234:237], v[238:241], v[242:245], v[234:237]
	ds_read_b128 v[238:241], v75
	ds_read_b128 v[242:245], v173
	s_waitcnt lgkmcnt(0)
	v_mfma_f32_16x16x32_bf16 v[234:237], v[238:241], v[242:245], v[234:237]
	ds_read_b128 v[238:241], v75 offset:64
	ds_read_b128 v[242:245], v173 offset:64
	s_waitcnt lgkmcnt(0)
	v_mfma_f32_16x16x32_bf16 v[234:237], v[238:241], v[242:245], v[234:237]
	ds_read_b128 v[238:241], v75 offset:128
	ds_read_b128 v[242:245], v173 offset:128
	s_waitcnt lgkmcnt(0)
	v_mfma_f32_16x16x32_bf16 v[234:237], v[238:241], v[242:245], v[234:237]
	ds_read_b128 v[238:241], v75 offset:192
	ds_read_b128 v[242:245], v173 offset:192
	s_waitcnt lgkmcnt(0)
	v_mfma_f32_16x16x32_bf16 v[234:237], v[238:241], v[242:245], v[234:237]
	s_nop 7
	v_cvt_pk_bf16_f32 v146, v234, s0
	ds_write_b16 v174, v146 offset:17408
	v_cvt_pk_bf16_f32 v146, v235, s0
	ds_write_b16 v174, v146 offset:17680
	v_cvt_pk_bf16_f32 v146, v236, s0
	ds_write_b16 v174, v146 offset:17952
	v_cvt_pk_bf16_f32 v146, v237, s0
	ds_write_b16 v174, v146 offset:18224
	ds_read_b128 v[234:237], v158
	ds_read_b128 v[238:241], v159
	s_waitcnt lgkmcnt(0)
	s_barrier
; __device__ __forceinline__ float bf2f(unsigned short v) { return __uint_as_float(((unsigned)v) << 16); }
; __device__ __forceinline__ float sigmoidf_(float x) { return __builtin_amdgcn_rcpf(1.0f + __expf(-x)); }
; template <bool PA>
; __device__ __forceinline__ void hgrn_scan(unsigned char* lds, const bf16* Q, const bf16* FFb, const bf16* FBb, const bf16* Ib, bf16* OFb, bf16* OBb, const float* lbp, float* segm, int slab, int tid) {
;     ...
;             float bl[16], kvv[16], qv[16]; float run = 1.f;
; #pragma unroll
;             for (int jj = 0; jj < 16; ++jj) { const float f = bf2f(fraw[jj]); const float fg = lb + (1.0f - lb) * sigmoidf_(f); run *= fg; bl[jj] = run; kvv[jj] = 1.0f - fg; qv[jj] = bf2f(qraw[jj]); }
;             tot[seg * 128 + c] = run;
;             { const size_t row = cbase + (dir ? 63 - jr : jr);
;               const u32x4_t w0 = *(const u32x4_t*)(Ib + row * 1024 + head * 128 + part * 16), w1 = *(const u32x4_t*)(Ib + row * 1024 + head * 128 + part * 16 + 8);
;     ...
;             { const int cc = 16 * wave + 4 * kq;
; #pragma unroll
;               for (int e = 0; e < 4; ++e) { const float ge = gtv[cc + e], ce = c2[cc + e];
; #pragma unroll
;                   for (int vt = 0; vt < 8; ++vt) S[vt][e] = ge * S[vt][e] + ce * kv[vt][e]; } }
;             __syncthreads();
;             if (!PA) { const size_t row = cbase + (dir ? 63 - jr : jr);
;                 *(u32x4_t*)(Op + row * 1024 + head * 128 + part * 16) = *(const u32x4_t*)(kin + jr * 136 + part * 16);
;                 *(u32x4_t*)(Op + row * 1024 + head * 128 + part * 16 + 8) = *(const u32x4_t*)(kin + jr * 136 + part * 16 + 8); }
	v_pk_mul_f32 v[40:41], v[40:41], v[240:241]
	v_pk_mul_f32 v[38:39], v[38:39], v[238:239]
	v_pk_mul_f32 v[36:37], v[36:37], v[240:241]
	v_pk_mul_f32 v[34:35], v[34:35], v[238:239]
	v_pk_fma_f32 v[28:29], v[28:29], v[236:237], v[40:41]
	v_pk_fma_f32 v[26:27], v[26:27], v[234:235], v[38:39]
	v_pk_fma_f32 v[32:33], v[32:33], v[236:237], v[36:37]
	v_pk_fma_f32 v[30:31], v[30:31], v[234:235], v[34:35]
	ds_read_b128 v[34:37], v97 offset:17408
	ds_read_b128 v[38:41], v133 offset:17424
	v_pk_mul_f32 v[48:49], v[48:49], v[240:241]
	v_pk_mul_f32 v[46:47], v[46:47], v[238:239]
	v_pk_fma_f32 v[8:9], v[8:9], v[236:237], v[48:49]
	v_pk_fma_f32 v[6:7], v[6:7], v[234:235], v[46:47]
	v_pk_mul_f32 v[46:47], v[52:53], v[240:241]
	v_pk_mul_f32 v[48:49], v[50:51], v[238:239]
	v_pk_fma_f32 v[12:13], v[12:13], v[236:237], v[46:47]
	v_pk_fma_f32 v[10:11], v[10:11], v[234:235], v[48:49]
	v_pk_mul_f32 v[46:47], v[56:57], v[240:241]
	v_pk_mul_f32 v[48:49], v[54:55], v[238:239]
	v_pk_mul_f32 v[42:43], v[42:43], v[238:239]
	v_pk_mul_f32 v[64:65], v[64:65], v[240:241]
	v_pk_mul_f32 v[62:63], v[62:63], v[238:239]
	v_pk_fma_f32 v[16:17], v[16:17], v[236:237], v[46:47]
	v_pk_fma_f32 v[14:15], v[14:15], v[234:235], v[48:49]
	v_pk_mul_f32 v[46:47], v[60:61], v[240:241]
	v_pk_mul_f32 v[48:49], v[58:59], v[238:239]
	v_pk_mul_f32 v[44:45], v[44:45], v[240:241]
	v_pk_fma_f32 v[22:23], v[22:23], v[234:235], v[42:43]
	v_lshl_add_u64 v[42:43], v[86:87], 1, v[84:85]
	v_pk_fma_f32 v[4:5], v[4:5], v[236:237], v[64:65]
	v_pk_fma_f32 v[2:3], v[2:3], v[234:235], v[62:63]
	v_pk_fma_f32 v[20:21], v[20:21], v[236:237], v[46:47]
	v_pk_fma_f32 v[18:19], v[18:19], v[234:235], v[48:49]
	v_pk_fma_f32 v[24:25], v[24:25], v[236:237], v[44:45]
	s_waitcnt lgkmcnt(1)
	global_store_dwordx4 v[42:43], v[34:37], off
	s_waitcnt lgkmcnt(0)
	global_store_dwordx4 v[42:43], v[38:41], off offset:16
	s_waitcnt vmcnt(29)
	v_mov_b32_e32 v42, v216
	s_waitcnt vmcnt(27)
	v_mov_b32_e32 v43, v218
	v_mov_b32_e32 v40, v81
	v_mov_b32_e32 v41, v215
	s_waitcnt vmcnt(25)
	v_mov_b32_e32 v44, v221
	s_waitcnt vmcnt(23)
	v_mov_b32_e32 v45, v222
	s_waitcnt vmcnt(21)
	v_mov_b32_e32 v46, v223
	s_waitcnt vmcnt(19)
	v_mov_b32_e32 v47, v224
	s_waitcnt vmcnt(17)
	v_mov_b32_e32 v48, v225
	s_waitcnt vmcnt(15)
	v_mov_b32_e32 v49, v226
	s_waitcnt vmcnt(13)
	v_mov_b32_e32 v50, v227
	s_waitcnt vmcnt(11)
	v_mov_b32_e32 v51, v228
	s_waitcnt vmcnt(9)
	v_mov_b32_e32 v53, v229
	s_waitcnt vmcnt(7)
	v_mov_b32_e32 v54, v230
	s_waitcnt vmcnt(5)
	v_mov_b32_e32 v55, v231
	s_waitcnt vmcnt(3)
	v_mov_b32_e32 v52, v232
	s_cbranch_vccnz .LBB0_668
.LBB0_676:
	v_lshlrev_b32_e32 v34, 16, v182
	v_mul_f32_e32 v34, 0xbfb8aa3b, v34
	v_exp_f32_e32 v34, v34
	s_add_i32 s12, s24, 1
	s_and_b64 s[10:11], s[56:57], exec
	s_cselect_b32 s10, s65, s12
	v_add_f32_e32 v34, 1.0, v34
	v_rcp_f32_e32 v34, v34
	v_lshl_add_u32 v38, s10, 6, v213
	v_ashrrev_i32_e32 v39, 31, v38
	v_lshlrev_b64 v[230:231], 11, v[38:39]
	v_lshl_add_u64 v[230:231], v[82:83], 0, v[230:231]
	global_load_dwordx4 v[222:225], v[230:231], off
	global_load_dwordx4 v[226:229], v[230:231], off offset:16
	s_add_i32 s65, s65, 1
	v_fma_f32 v58, v211, v34, v210
	v_lshlrev_b32_e32 v34, 16, v184
	v_mul_f32_e32 v34, 0xbfb8aa3b, v34
	v_exp_f32_e32 v34, v34
	s_cmp_ge_i32 s65, s67
	s_cselect_b64 s[10:11], -1, 0
	s_and_b64 vcc, exec, s[10:11]
	v_add_f32_e32 v34, 1.0, v34
	v_rcp_f32_e32 v34, v34
	s_nop 0
	v_fma_f32 v239, v211, v34, v210
	v_lshlrev_b32_e32 v34, 16, v185
	v_mul_f32_e32 v34, 0xbfb8aa3b, v34
	v_exp_f32_e32 v34, v34
	v_mul_f32_e32 v64, v58, v239
	v_add_f32_e32 v34, 1.0, v34
	v_rcp_f32_e32 v34, v34
	s_nop 0
	v_fma_f32 v240, v211, v34, v210
	v_lshlrev_b32_e32 v34, 16, v186
	v_mul_f32_e32 v34, 0xbfb8aa3b, v34
	v_exp_f32_e32 v34, v34
	v_mul_f32_e32 v62, v64, v240
	v_add_f32_e32 v34, 1.0, v34
	v_rcp_f32_e32 v34, v34
	s_nop 0
	v_fma_f32 v241, v211, v34, v210
	v_lshlrev_b32_e32 v34, 16, v193
	v_mul_f32_e32 v34, 0xbfb8aa3b, v34
	v_exp_f32_e32 v34, v34
	v_mul_f32_e32 v234, v62, v241
	v_add_f32_e32 v34, 1.0, v34
	v_rcp_f32_e32 v34, v34
	s_nop 0
	v_fma_f32 v242, v211, v34, v210
	v_lshlrev_b32_e32 v34, 16, v195
	v_mul_f32_e32 v34, 0xbfb8aa3b, v34
	v_exp_f32_e32 v34, v34
	v_mul_f32_e32 v237, v234, v242
	v_add_f32_e32 v34, 1.0, v34
	v_rcp_f32_e32 v34, v34
	s_nop 0
	v_fma_f32 v243, v211, v34, v210
	v_lshlrev_b32_e32 v34, 16, v205
	v_mul_f32_e32 v34, 0xbfb8aa3b, v34
	v_exp_f32_e32 v34, v34
	v_mul_f32_e32 v238, v237, v243
	v_add_f32_e32 v34, 1.0, v34
	v_rcp_f32_e32 v34, v34
	s_nop 0
	v_fma_f32 v244, v211, v34, v210
	v_lshlrev_b32_e32 v34, 16, v206
	v_mul_f32_e32 v34, 0xbfb8aa3b, v34
	v_exp_f32_e32 v34, v34
	v_mul_f32_e32 v236, v238, v244
	v_add_f32_e32 v34, 1.0, v34
	v_rcp_f32_e32 v34, v34
	s_nop 0
	v_fma_f32 v245, v211, v34, v210
	v_lshlrev_b32_e32 v34, 16, v207
	v_mul_f32_e32 v34, 0xbfb8aa3b, v34
	v_exp_f32_e32 v34, v34
	v_mul_f32_e32 v235, v236, v245
	v_add_f32_e32 v34, 1.0, v34
	v_rcp_f32_e32 v34, v34
	s_nop 0
	v_fma_f32 v246, v211, v34, v210
	v_lshlrev_b32_e32 v34, 16, v208
	v_mul_f32_e32 v34, 0xbfb8aa3b, v34
	v_exp_f32_e32 v34, v34
	v_mul_f32_e32 v233, v235, v246
	v_add_f32_e32 v34, 1.0, v34
	v_rcp_f32_e32 v34, v34
	s_nop 0
	v_fma_f32 v247, v211, v34, v210
	v_lshlrev_b32_e32 v34, 16, v209
	v_mul_f32_e32 v34, 0xbfb8aa3b, v34
	v_exp_f32_e32 v34, v34
	v_mul_f32_e32 v65, v233, v247
	v_add_f32_e32 v34, 1.0, v34
	v_rcp_f32_e32 v34, v34
	s_nop 0
	v_fma_f32 v248, v211, v34, v210
	v_lshlrev_b32_e32 v34, 16, v212
	v_mul_f32_e32 v34, 0xbfb8aa3b, v34
	v_exp_f32_e32 v34, v34
	v_mul_f32_e32 v63, v65, v248
	v_add_f32_e32 v34, 1.0, v34
	v_rcp_f32_e32 v34, v34
	s_nop 0
	v_fma_f32 v249, v211, v34, v210
	v_lshlrev_b32_e32 v34, 16, v214
	v_mul_f32_e32 v34, 0xbfb8aa3b, v34
	v_exp_f32_e32 v34, v34
	v_mul_f32_e32 v61, v63, v249
	v_add_f32_e32 v34, 1.0, v34
	v_rcp_f32_e32 v34, v34
	s_nop 0
	v_fma_f32 v250, v211, v34, v210
	v_lshlrev_b32_e32 v34, 16, v217
	v_mul_f32_e32 v34, 0xbfb8aa3b, v34
	v_exp_f32_e32 v34, v34
	v_mul_f32_e32 v60, v61, v250
	v_add_f32_e32 v34, 1.0, v34
	v_rcp_f32_e32 v34, v34
	s_nop 0
	v_fma_f32 v251, v211, v34, v210
	v_lshlrev_b32_e32 v34, 16, v219
	v_mul_f32_e32 v34, 0xbfb8aa3b, v34
	v_exp_f32_e32 v34, v34
	v_mul_f32_e32 v59, v60, v251
	v_add_f32_e32 v34, 1.0, v34
	v_rcp_f32_e32 v34, v34
	s_nop 0
	v_fma_f32 v252, v211, v34, v210
	s_waitcnt vmcnt(2)
; __device__ __forceinline__ float bf2f(unsigned short v) { return __uint_as_float(((unsigned)v) << 16); }
; __device__ __forceinline__ float sigmoidf_(float x) { return __builtin_amdgcn_rcpf(1.0f + __expf(-x)); }
; template <bool PA>
; __device__ __forceinline__ void hgrn_scan(unsigned char* lds, const bf16* Q, const bf16* FFb, const bf16* FBb, const bf16* Ib, bf16* OFb, bf16* OBb, const float* lbp, float* segm, int slab, int tid) {
;     ...
;             for (int jj = 0; jj < 16; ++jj) { const float f = bf2f(fraw[jj]); const float fg = lb + (1.0f - lb) * sigmoidf_(f); run *= fg; bl[jj] = run; kvv[jj] = 1.0f - fg; qv[jj] = bf2f(qraw[jj]); }
;             tot[seg * 128 + c] = run;
;             { const size_t row = cbase + (dir ? 63 - jr : jr);
;               const u32x4_t w0 = *(const u32x4_t*)(Ib + row * 1024 + head * 128 + part * 16), w1 = *(const u32x4_t*)(Ib + row * 1024 + head * 128 + part * 16 + 8);
;               const unsigned wa[8] = {w0.x, w0.y, w0.z, w0.w, w1.x, w1.y, w1.z, w1.w};
; #pragma unroll
;               for (int q = 0; q < 8; ++q) { iT[(part * 16 + 2 * q) * 72 + jr] = (bf16)(wa[q] & 0xffff); iT[(part * 16 + 2 * q + 1) * 72 + jr] = (bf16)(wa[q] >> 16); } }
;             if (p + 1 < p1) { const int nb = seqbase + (dir ? nch - 2 - p : p + 1) * 64;
; #pragma unroll
;                 for (int jj = 0; jj < 16; ++jj) { const int j = 16 * seg + jj; const unsigned bo = ((unsigned)(nb + (dir ? 63 - j : j)) * 1024u + (unsigned)hc) * 2u; qraw[jj] = PA ? (unsigned short)0 : *(const unsigned short*)((const char*)Q + bo); fraw[jj] = *(const unsigned short*)((const char*)Fp + bo); } }
	v_lshlrev_b32_e32 v34, 16, v220
	v_mul_f32_e32 v34, 0xbfb8aa3b, v34
	v_exp_f32_e32 v34, v34
	v_mul_f32_e32 v57, v59, v252
	v_add_f32_e32 v34, 1.0, v34
	v_rcp_f32_e32 v34, v34
	s_nop 0
	v_fma_f32 v146, v211, v34, v210
	v_mul_f32_e32 v56, v57, v146
	ds_write_b32 v90, v56
	s_waitcnt vmcnt(1)
	ds_write_b16 v129, v222 offset:62464
	ds_write_b16_d16_hi v130, v222 offset:62608
	ds_write_b16 v129, v223 offset:62752
	ds_write_b16_d16_hi v130, v223 offset:62896
	ds_write_b16 v134, v224 offset:63040
	ds_write_b16_d16_hi v135, v224 offset:63184
	ds_write_b16 v134, v225 offset:63328
	ds_write_b16_d16_hi v135, v225 offset:63472
	s_waitcnt vmcnt(0)
	ds_write_b16 v134, v226 offset:63616
	ds_write_b16_d16_hi v135, v226 offset:63760
	ds_write_b16 v134, v227 offset:63904
	ds_write_b16_d16_hi v135, v227 offset:64048
	ds_write_b16 v129, v228 offset:64192
	ds_write_b16_d16_hi v130, v228 offset:64336
	ds_write_b16 v129, v229 offset:64480
	ds_write_b16_d16_hi v130, v229 offset:64624
	s_cbranch_vccnz .LBB0_678
	s_and_b64 s[12:13], s[56:57], exec
	s_cselect_b32 s12, s65, s24
	s_lshl_b32 s12, s12, 6
	s_add_i32 s12, s12, s66
	v_add_u32_e32 v34, s12, v0
	v_lshl_or_b32 v34, v34, 11, v175
	v_add_u32_e32 v35, s12, v176
	v_add_u32_e32 v36, s12, v177
	v_add_u32_e32 v37, s12, v178
	v_lshl_or_b32 v35, v35, 11, v175
	v_lshl_or_b32 v36, v36, 11, v175
	v_lshl_or_b32 v37, v37, 11, v175
	global_load_ushort v81, v34, s[16:17]
	global_load_ushort v182, v34, s[8:9]
	global_load_ushort v215, v35, s[16:17]
	global_load_ushort v184, v35, s[8:9]
	global_load_ushort v216, v36, s[16:17]
	global_load_ushort v185, v36, s[8:9]
	global_load_ushort v218, v37, s[16:17]
	global_load_ushort v186, v37, s[8:9]
	v_add_u32_e32 v34, s12, v179
	v_lshl_or_b32 v34, v34, 11, v175
	v_add_u32_e32 v35, s12, v180
	v_add_u32_e32 v36, s12, v181
	v_add_u32_e32 v37, s12, v183
	v_lshl_or_b32 v35, v35, 11, v175
	v_lshl_or_b32 v36, v36, 11, v175
	v_lshl_or_b32 v37, v37, 11, v175
	global_load_ushort v221, v34, s[16:17]
	global_load_ushort v193, v34, s[8:9]
	global_load_ushort v222, v35, s[16:17]
	global_load_ushort v195, v35, s[8:9]
	global_load_ushort v223, v36, s[16:17]
	global_load_ushort v205, v36, s[8:9]
	global_load_ushort v224, v37, s[16:17]
	global_load_ushort v206, v37, s[8:9]
	v_add_u32_e32 v34, s12, v187
	v_lshl_or_b32 v34, v34, 11, v175
	v_add_u32_e32 v35, s12, v188
	v_add_u32_e32 v36, s12, v189
	v_add_u32_e32 v37, s12, v190
	v_lshl_or_b32 v35, v35, 11, v175
	v_lshl_or_b32 v36, v36, 11, v175
	v_lshl_or_b32 v37, v37, 11, v175
	global_load_ushort v225, v34, s[16:17]
	global_load_ushort v207, v34, s[8:9]
	global_load_ushort v226, v35, s[16:17]
	global_load_ushort v208, v35, s[8:9]
	global_load_ushort v227, v36, s[16:17]
	global_load_ushort v209, v36, s[8:9]
	global_load_ushort v228, v37, s[16:17]
	global_load_ushort v212, v37, s[8:9]
	v_add_u32_e32 v34, s12, v191
	v_lshl_or_b32 v34, v34, 11, v175
	v_add_u32_e32 v35, s12, v192
	v_add_u32_e32 v36, s12, v194
	v_add_u32_e32 v37, s12, v204
	v_lshl_or_b32 v35, v35, 11, v175
	v_lshl_or_b32 v36, v36, 11, v175
	v_lshl_or_b32 v37, v37, 11, v175
	global_load_ushort v229, v34, s[16:17]
	global_load_ushort v214, v34, s[8:9]
	global_load_ushort v230, v35, s[16:17]
	global_load_ushort v217, v35, s[8:9]
	global_load_ushort v231, v36, s[16:17]
	global_load_ushort v219, v36, s[8:9]
	global_load_ushort v232, v37, s[16:17]
	global_load_ushort v220, v37, s[8:9]

; __device__ __forceinline__ unsigned f2bf(float f) { return pk2(f, 0.f) & 0xffffu; }
; template <bool PA>
; __device__ __forceinline__ void hgrn_scan(unsigned char* lds, const bf16* Q, const bf16* FFb, const bf16* FBb, const bf16* Ib, bf16* OFb, bf16* OBb, const float* lbp, float* segm, int slab, int tid) {
;     ...
;             const float t0 = tot[c], t1 = tot[128 + c], t2 = tot[256 + c], t3 = tot[384 + c];
;             const float off = seg == 0 ? 1.f : (seg == 1 ? t0 : (seg == 2 ? t0 * t1 : t0 * t1 * t2));
;             const float aref = t0 * t1, alast = (t0 * t1) * (t2 * t3); const float iaref = __builtin_amdgcn_rcpf(aref);
; #pragma unroll
;             for (int jj = 0; jj < 16; ++jj) { const int j = 16 * seg + jj; const float at = off * bl[jj];
;                 const float ke = kvv[jj] * (aref * __builtin_amdgcn_rcpf(at)); const bf16 kb = (bf16)f2bf(ke); kinT[c * 72 + j] = kb;
;                 if (!PA) { const float qe = qv[jj] * (at * iaref); qin[j * 136 + c] = (bf16)f2bf(qe); kin[j * 136 + c] = kb; } }
;             if (seg == 0) { c1[c] = aref; c2[c] = alast * iaref; gtv[c] = alast; gprod *= alast; }
.LBB0_686:
	s_or_b64 exec, exec, s[12:13]
	s_waitcnt lgkmcnt(1)
	v_mul_f32_e32 v36, v36, v37
	v_rcp_f32_e32 v37, v36
	v_lshlrev_b64 v[86:87], 10, v[38:39]
	v_sub_f32_e32 v38, 1.0, v58
	v_mul_f32_e32 v58, v58, v147
	v_sub_f32_e32 v201, 1.0, v241
	v_sub_f32_e32 v241, 1.0, v244
	v_sub_f32_e32 v244, 1.0, v247
	v_sub_f32_e32 v247, 1.0, v250
	v_rcp_f32_e32 v250, v58
	v_lshlrev_b32_e32 v39, 16, v40
	v_mul_f32_e32 v58, v37, v58
	v_mul_f32_e32 v39, v58, v39
	v_mul_f32_e32 v58, v64, v147
	v_rcp_f32_e32 v64, v58
	v_mul_f32_e32 v250, v36, v250
	v_mul_f32_e32 v38, v38, v250
	v_cvt_pk_bf16_f32 v38, v38, s0
	v_cvt_pk_bf16_f32 v39, v39, s0
	v_sub_f32_e32 v40, 1.0, v239
	ds_write_b16 v131, v38 offset:34816
	ds_write_b16 v132, v39
	ds_write_b16 v132, v38 offset:17408
	v_mul_f32_e32 v38, v36, v64
	v_lshlrev_b32_e32 v41, 16, v41
	v_mul_f32_e32 v38, v40, v38
	v_mul_f32_e32 v39, v37, v58
	v_mul_f32_e32 v40, v62, v147
	v_mul_f32_e32 v39, v39, v41
	v_rcp_f32_e32 v41, v40
	v_cvt_pk_bf16_f32 v38, v38, s0
	v_cvt_pk_bf16_f32 v39, v39, s0
	ds_write_b16 v131, v38 offset:34818
	ds_write_b16 v132, v39 offset:272
	ds_write_b16 v132, v38 offset:17680
	v_mul_f32_e32 v39, v37, v40
	v_mul_f32_e32 v40, v234, v147
	v_sub_f32_e32 v200, 1.0, v240
	v_lshlrev_b32_e32 v42, 16, v42
	v_mul_f32_e32 v38, v36, v41
	v_rcp_f32_e32 v41, v40
	v_mul_f32_e32 v38, v200, v38
	v_mul_f32_e32 v39, v39, v42
	v_cvt_pk_bf16_f32 v38, v38, s0
	v_cvt_pk_bf16_f32 v39, v39, s0
	ds_write_b16 v131, v38 offset:34820
	ds_write_b16 v132, v39 offset:544
	ds_write_b16 v132, v38 offset:17952
	v_mul_f32_e32 v39, v37, v40
	v_mul_f32_e32 v40, v237, v147
	v_lshlrev_b32_e32 v43, 16, v43
	v_mul_f32_e32 v38, v36, v41
	v_rcp_f32_e32 v41, v40
	v_mul_f32_e32 v38, v201, v38
	v_mul_f32_e32 v39, v39, v43
	v_cvt_pk_bf16_f32 v38, v38, s0
	v_cvt_pk_bf16_f32 v39, v39, s0
	ds_write_b16 v131, v38 offset:34822
	ds_write_b16 v132, v39 offset:816
	ds_write_b16 v132, v38 offset:18224
	v_mul_f32_e32 v39, v37, v40
	v_mul_f32_e32 v40, v238, v147
	v_sub_f32_e32 v239, 1.0, v242
	v_lshlrev_b32_e32 v44, 16, v44
	v_mul_f32_e32 v38, v36, v41
	v_rcp_f32_e32 v41, v40
	v_mul_f32_e32 v38, v239, v38
	v_mul_f32_e32 v39, v39, v44
	v_cvt_pk_bf16_f32 v38, v38, s0
	v_cvt_pk_bf16_f32 v39, v39, s0
	ds_write_b16 v131, v38 offset:34824
	ds_write_b16 v137, v39 offset:1088
	ds_write_b16 v137, v38 offset:18496
	v_mul_f32_e32 v39, v37, v40
	v_mul_f32_e32 v40, v236, v147
	v_sub_f32_e32 v240, 1.0, v243
	v_lshlrev_b32_e32 v45, 16, v45
	v_mul_f32_e32 v38, v36, v41
	v_rcp_f32_e32 v41, v40
	v_mul_f32_e32 v38, v240, v38
	v_mul_f32_e32 v39, v39, v45
	v_cvt_pk_bf16_f32 v38, v38, s0
	v_cvt_pk_bf16_f32 v39, v39, s0
	ds_write_b16 v131, v38 offset:34826
	ds_write_b16 v137, v39 offset:1360
	ds_write_b16 v137, v38 offset:18768
	v_mul_f32_e32 v39, v37, v40
	v_mul_f32_e32 v40, v235, v147
	v_lshlrev_b32_e32 v46, 16, v46
	v_mul_f32_e32 v38, v36, v41
	v_rcp_f32_e32 v41, v40
	v_mul_f32_e32 v38, v241, v38
	v_mul_f32_e32 v39, v39, v46
	v_cvt_pk_bf16_f32 v38, v38, s0
	v_cvt_pk_bf16_f32 v39, v39, s0
	ds_write_b16 v131, v38 offset:34828
	ds_write_b16 v137, v39 offset:1632
	ds_write_b16 v137, v38 offset:19040
	v_mul_f32_e32 v39, v37, v40
	v_mul_f32_e32 v40, v233, v147
	v_sub_f32_e32 v242, 1.0, v245
	v_lshlrev_b32_e32 v47, 16, v47
	v_mul_f32_e32 v38, v36, v41
	v_rcp_f32_e32 v41, v40
	v_mul_f32_e32 v38, v242, v38
	v_mul_f32_e32 v39, v39, v47
	v_cvt_pk_bf16_f32 v38, v38, s0
	v_cvt_pk_bf16_f32 v39, v39, s0
	ds_write_b16 v131, v38 offset:34830
	ds_write_b16 v137, v39 offset:1904
	ds_write_b16 v137, v38 offset:19312
	v_mul_f32_e32 v39, v37, v40
	v_mul_f32_e32 v40, v65, v147
	v_sub_f32_e32 v243, 1.0, v246
	v_lshlrev_b32_e32 v48, 16, v48
	v_mul_f32_e32 v38, v36, v41
	v_rcp_f32_e32 v41, v40
	v_mul_f32_e32 v38, v243, v38
	v_mul_f32_e32 v39, v39, v48
	v_cvt_pk_bf16_f32 v38, v38, s0
	v_cvt_pk_bf16_f32 v39, v39, s0
	ds_write_b16 v136, v38 offset:34832
	ds_write_b16 v137, v39 offset:2176
	ds_write_b16 v137, v38 offset:19584
	v_mul_f32_e32 v39, v37, v40
	v_mul_f32_e32 v40, v63, v147
	v_lshlrev_b32_e32 v49, 16, v49
	v_mul_f32_e32 v38, v36, v41
	v_rcp_f32_e32 v41, v40
	v_mul_f32_e32 v38, v244, v38
	v_mul_f32_e32 v39, v39, v49
	v_cvt_pk_bf16_f32 v38, v38, s0
	v_cvt_pk_bf16_f32 v39, v39, s0
	ds_write_b16 v136, v38 offset:34834
	ds_write_b16 v137, v39 offset:2448
	ds_write_b16 v137, v38 offset:19856
	v_mul_f32_e32 v39, v37, v40
	v_mul_f32_e32 v40, v61, v147
	v_sub_f32_e32 v245, 1.0, v248
	v_lshlrev_b32_e32 v50, 16, v50
	v_mul_f32_e32 v38, v36, v41
	v_rcp_f32_e32 v41, v40
	v_mul_f32_e32 v38, v245, v38
	v_mul_f32_e32 v39, v39, v50
	v_cvt_pk_bf16_f32 v38, v38, s0
	v_cvt_pk_bf16_f32 v39, v39, s0
	ds_write_b16 v136, v38 offset:34836
	ds_write_b16 v137, v39 offset:2720
	ds_write_b16 v137, v38 offset:20128
	v_mul_f32_e32 v39, v37, v40
	v_mul_f32_e32 v40, v60, v147
	v_sub_f32_e32 v246, 1.0, v249
	v_lshlrev_b32_e32 v51, 16, v51
	v_mul_f32_e32 v38, v36, v41
	v_rcp_f32_e32 v41, v40
	v_mul_f32_e32 v38, v246, v38
	v_mul_f32_e32 v39, v39, v51
	v_cvt_pk_bf16_f32 v38, v38, s0
	v_cvt_pk_bf16_f32 v39, v39, s0
	ds_write_b16 v136, v38 offset:34838
	ds_write_b16 v137, v39 offset:2992
	ds_write_b16 v137, v38 offset:20400
	v_mul_f32_e32 v39, v37, v40
	v_mul_f32_e32 v40, v59, v147
	v_lshlrev_b32_e32 v53, 16, v53
	v_mul_f32_e32 v38, v36, v41
	v_rcp_f32_e32 v41, v40
	v_mul_f32_e32 v38, v247, v38
	v_mul_f32_e32 v39, v39, v53
	v_cvt_pk_bf16_f32 v38, v38, s0
	v_cvt_pk_bf16_f32 v39, v39, s0
	ds_write_b16 v136, v38 offset:34840
	ds_write_b16 v132, v39 offset:3264
	ds_write_b16 v132, v38 offset:20672
	v_mul_f32_e32 v39, v37, v40
	v_mul_f32_e32 v40, v57, v147
	v_sub_f32_e32 v248, 1.0, v251
	v_lshlrev_b32_e32 v54, 16, v54
	v_mul_f32_e32 v38, v36, v41
	v_rcp_f32_e32 v41, v40
	v_mul_f32_e32 v38, v248, v38
	v_mul_f32_e32 v39, v39, v54
	v_cvt_pk_bf16_f32 v38, v38, s0
	v_cvt_pk_bf16_f32 v39, v39, s0
	ds_write_b16 v136, v38 offset:34842
	ds_write_b16 v132, v39 offset:3536
	ds_write_b16 v132, v38 offset:20944
	v_mul_f32_e32 v39, v37, v40
	v_mul_f32_e32 v40, v56, v147
	v_mul_f32_e32 v38, v36, v41
	v_rcp_f32_e32 v41, v40
	v_sub_f32_e32 v249, 1.0, v252
	v_lshlrev_b32_e32 v55, 16, v55
	v_mul_f32_e32 v38, v249, v38
	v_mul_f32_e32 v39, v39, v55
	v_cvt_pk_bf16_f32 v38, v38, s0
	v_cvt_pk_bf16_f32 v39, v39, s0
	v_sub_f32_e32 v146, 1.0, v146
	v_lshlrev_b32_e32 v52, 16, v52
	ds_write_b16 v136, v38 offset:34844
	ds_write_b16 v132, v39 offset:3808
	ds_write_b16 v132, v38 offset:21216
	v_mul_f32_e32 v38, v36, v41
	v_mul_f32_e32 v39, v37, v40
	v_mul_f32_e32 v38, v146, v38
	v_mul_f32_e32 v39, v39, v52
	v_cvt_pk_bf16_f32 v38, v38, s0
	v_cvt_pk_bf16_f32 v39, v39, s0
	ds_write_b16 v136, v38 offset:34846
	ds_write_b16 v132, v39 offset:4080
	ds_write_b16 v132, v38 offset:21488
	s_and_saveexec_b64 s[12:13], s[36:37]
	s_cbranch_execz .LBB0_675
	s_waitcnt lgkmcnt(14)
	v_mul_f32_e32 v34, v34, v35
	v_mul_f32_e32 v34, v36, v34
	v_mul_f32_e32 v35, v37, v34
	ds_write_b32 v95, v36
	ds_write_b32 v94, v35
	ds_write_b32 v93, v34
	s_branch .LBB0_675
